# MIX: partner workgroup no longer holds off while a sample scan runs on its CU (the lighter scan step tolerates the sharing)
# speedup vs baseline: 1.3439x; 1.0319x over previous
.LBB0_102:
	v_readlane_b32 s2, v253, 1
	v_readlane_b32 s3, v253, 2
	s_barrier
	s_and_saveexec_b64 s[0:1], s[2:3]
	s_cbranch_execz .Lq_sync
	s_branch .Lq_fetch
	s_cmp_eq_u32 s98, 1
	s_cbranch_scc0 .Lq_fetch
	s_movk_i32 s25, 1000
